# inproj: tile row-scale (rstd) block moved after the first 8 LDS-DMA loads so its latency overlaps theirs
# speedup vs baseline: 1.0200x; 1.0200x over previous
; DI int tid() { int t = __builtin_amdgcn_workitem_id_x(); asm volatile("" : "+v"(t)); return t; }
; #define STAGE(P, BASE, br, kt) do { const bf16_t* g_ = (BASE) + (size_t)(br) * K + (size_t)(kt) * 64; \
;         _Pragma("unroll") for (int i_ = 0; i_ < 2; ++i_) \
;             __builtin_amdgcn_global_load_lds((const unsigned*)(g_ + gofs[i_]), (lds_ptr_t)((P) + wb + i_ * 8192), 16, 0, 0); } while (0)
; #define BAR __builtin_amdgcn_s_barrier()
; #define STAGE(P, BASE, br, kt) do { const int sg_ = (kt) >> 3; const bf16_t* g_ = (sg_ == 0 ? BASE##0 : sg_ == 1 ? BASE##1 : BASE##2) + (size_t)(br) * K + (size_t)((kt) & 7) * 64; \
;         _Pragma("unroll") for (int i_ = 0; i_ < 2; ++i_) \
;             __builtin_amdgcn_global_load_lds((const unsigned*)(g_ + gofs[i_]), (lds_ptr_t)((P) + wb + i_ * 8192), 16, 0, 0); } while (0)
; #define BAR __builtin_amdgcn_s_barrier()
; DI void gemm8(f32x4 (&acc)[2][2][4][2], const bf16_t* __restrict__ Rm, const bf16_t* __restrict__ Cm, int K, char* shm) {
;     ...
;     for (int i = 0; i < 2; ++i) { int r_, c_; stage_rc(t * 16 + i * 8192, r_, c_); gofs[i] = r_ * K + c_; }
;     const int wb = wid * 1024;
;     ...
; #pragma unroll
;     for (int a_ = 0; a_ < 2; ++a_)
; #pragma unroll
;         for (int b_ = 0; b_ < 2; ++b_)
; #pragma unroll
;             for (int m = 0; m < 4; ++m) { acc[a_][b_][m][0] = (f32x4){0.f, 0.f, 0.f, 0.f}; acc[a_][b_][m][1] = (f32x4){0.f, 0.f, 0.f, 0.f}; }
;     bf16x8 At[4][2], B0[2][2], B1[2][2];
;     const int nt = K >> 6;
;     STAGE(SB(0, 0), Cm, 0, 0); STAGE(SA(0, 0), Rm, 0, 0);
;     STAGE(SB(0, 1), Cm, 128, 0); STAGE(SA(0, 1), Rm, 128, 0);
;     if (wr == 1) BAR;
; DI void tile_rstd(const float* __restrict__ ssq, int m0, char* lds) {
;     __syncthreads();
;     const int t = tid();
;     if (t < 256) {
;         const f32x4* p = (const f32x4*)(ssq + (size_t)(m0 + t) * 16);
;         const f32x4 a = p[0], b = p[1], c = p[2], d = p[3];
;         const float sm = ((a[0] + a[1]) + (a[2] + a[3])) + ((b[0] + b[1]) + (b[2] + b[3])) + ((c[0] + c[1]) + (c[2] + c[3])) + ((d[0] + d[1]) + (d[2] + d[3]));
;         ((float*)(lds + LDS_RS))[t] = __builtin_amdgcn_rsqf(sm * (1.f / 1024.f) + kEps);
;     }
.LBB0_172:
	s_lshr_b32 s2, s55, 2
	s_and_b32 s58, s2, 64
	s_lshl_b32 s2, s55, 3
	s_and_b32 s59, s2, 56
	s_or_b32 s2, s58, s59
	s_bfe_u32 s64, s55, 0x30003
	s_or_b32 s15, s2, s64
	v_mov_b32_e32 v0, v162
	s_lshl_b32 s56, s15, 8
	s_ashr_i32 s65, s55, 7
	s_and_b32 s2, s65, -4
	s_bfe_u32 s14, s55, 0x20006
	s_or_b32 s57, s2, s14
	s_lshl_b32 s82, s57, 8
	s_cmp_gt_i32 s57, 7
	s_cselect_b64 s[2:3], -1, 0
	s_add_i32 s6, s82, 0xfffff800
	s_and_b32 s6, s6, 0xfffff600
	s_cmpk_eq_i32 s6, 0x400
	s_cselect_b64 s[6:7], -1, 0
	s_and_b64 s[2:3], s[2:3], s[6:7]
	s_andn2_b64 vcc, exec, s[2:3]
	s_mov_b64 s[6:7], -1
	s_cbranch_vccz .LBB0_310
	v_mov_b32_e32 v0, v162
	s_ashr_i32 s3, s82, 31
	v_ashrrev_i32_e32 v3, 31, v0
	v_lshrrev_b32_e32 v3, 26, v3
	v_add_u32_e32 v3, v0, v3
	v_ashrrev_i32_e32 v10, 6, v3
	v_bfe_i32 v3, v0, 27, 1
	v_lshlrev_b32_e32 v2, 4, v0
	v_lshrrev_b32_e32 v3, 22, v3
	v_add_u32_e32 v3, v2, v3
	v_and_b32_e32 v3, 0xfffffc00, v3
	v_sub_u32_e32 v3, v2, v3
	v_lshrrev_b32_e32 v4, 4, v3
	v_bitop3_b32 v4, v4, v3, 32 bitop3:0x6c
	v_ashrrev_i32_e32 v3, 31, v3
	v_lshrrev_b32_e32 v3, 26, v3
	v_lshlrev_b32_e32 v5, 3, v10
	v_add_u32_e32 v3, v4, v3
	v_and_b32_e32 v5, 0x3ffff0, v5
	v_ashrrev_i32_e32 v11, 6, v3
	v_add_u32_e32 v3, v11, v5
	v_lshlrev_b32_e32 v5, 5, v10
	v_and_b32_e32 v12, 32, v5
	v_mul_i32_i24_e32 v5, 64, v11
	v_sub_u32_e32 v4, v4, v5
	v_ashrrev_i16_sdwa v13, v175, sext(v4) dst_sel:DWORD dst_unused:UNUSED_PAD src0_sel:DWORD src1_sel:BYTE_0
	v_lshl_or_b32 v3, v3, 10, v12
	v_add_u32_e32 v2, 0x2000, v2
	v_add_u32_sdwa v130, v3, sext(v13) dst_sel:DWORD dst_unused:UNUSED_PAD src0_sel:DWORD src1_sel:WORD_0
	v_ashrrev_i32_e32 v3, 31, v2
	v_lshrrev_b32_e32 v3, 22, v3
	v_add_u32_e32 v3, v2, v3
	v_ashrrev_i32_e32 v14, 10, v3
	v_mul_i32_i24_e32 v3, 0x400, v14
	v_sub_u32_e32 v2, v2, v3
	v_lshrrev_b32_e32 v3, 4, v2
	v_bitop3_b32 v2, v3, v2, 32 bitop3:0x6c
	v_ashrrev_i32_e32 v4, 31, v2
	v_lshrrev_b32_e32 v4, 26, v4
	s_mov_b32 s2, s82
	v_lshlrev_b32_e32 v3, 3, v14
	v_add_u32_e32 v4, v2, v4
	s_lshl_b64 s[2:3], s[2:3], 11
	v_and_b32_e32 v3, 0x3ffff0, v3
	v_ashrrev_i32_e32 v16, 6, v4
	v_lshlrev_b32_e32 v5, 5, v14
	v_and_b32_e32 v4, 0xc0, v4
	s_add_u32 s6, s31, s2
	v_ashrrev_i32_e32 v15, 6, v0
	v_add_u32_e32 v3, v16, v3
	v_and_b32_e32 v17, 32, v5
	v_sub_u32_e32 v2, v2, v4
	s_addc_u32 s7, s54, s3
	s_lshl_b32 s2, s15, 19
	v_ashrrev_i16_sdwa v18, v175, sext(v2) dst_sel:DWORD dst_unused:UNUSED_PAD src0_sel:DWORD src1_sel:BYTE_0
	v_lshl_or_b32 v2, v3, 10, v17
	v_lshlrev_b32_e32 v146, 10, v15
	s_add_u32 s8, s34, s2
	v_add_u32_sdwa v132, v2, sext(v18) dst_sel:DWORD dst_unused:UNUSED_PAD src0_sel:DWORD src1_sel:WORD_0
	v_add_u32_e32 v147, 0x10000, v146
	v_ashrrev_i32_e32 v131, 31, v130
	s_addc_u32 s9, s28, 0
	v_lshlrev_b64 v[20:21], 1, v[130:131]
	v_readfirstlane_b32 s2, v147
	v_ashrrev_i32_e32 v133, 31, v132
	v_add_u32_e32 v148, 0x12000, v146
	v_lshl_add_u64 v[2:3], s[8:9], 0, v[20:21]
	s_mov_b32 m0, s2
	v_lshlrev_b64 v[22:23], 1, v[132:133]
	v_readfirstlane_b32 s2, v148
	global_load_lds_dwordx4 v[2:3], off
	v_lshl_add_u64 v[6:7], s[8:9], 0, v[22:23]
	s_mov_b32 m0, s2
	v_readfirstlane_b32 s2, v146
	v_add_u32_e32 v150, 0x2000, v146
	global_load_lds_dwordx4 v[6:7], off
	v_lshl_add_u64 v[8:9], s[6:7], 0, v[20:21]
	s_mov_b32 m0, s2
	v_readfirstlane_b32 s2, v150
	global_load_lds_dwordx4 v[8:9], off
	s_mov_b32 m0, s2
	s_add_u32 s2, s8, 0x40000
	v_add_u32_e32 v151, 0x14000, v146
	v_lshl_add_u64 v[4:5], s[6:7], 0, v[22:23]
	s_addc_u32 s3, s9, 0
	v_readfirstlane_b32 s10, v151
	global_load_lds_dwordx4 v[4:5], off
	v_lshl_add_u64 v[24:25], s[2:3], 0, v[20:21]
	s_mov_b32 m0, s10
	v_add_u32_e32 v152, 0x16000, v146
	global_load_lds_dwordx4 v[24:25], off
	v_lshl_add_u64 v[24:25], s[2:3], 0, v[22:23]
	v_readfirstlane_b32 s2, v152
	s_mov_b32 m0, s2
	s_add_u32 s2, s6, 0x40000
	v_add_u32_e32 v153, 0x4000, v146
	s_addc_u32 s3, s7, 0
	v_readfirstlane_b32 s10, v153
	global_load_lds_dwordx4 v[24:25], off
	v_lshl_add_u64 v[20:21], s[2:3], 0, v[20:21]
	s_mov_b32 m0, s10
	v_add_u32_e32 v155, 0x6000, v146
	global_load_lds_dwordx4 v[20:21], off
	v_lshl_add_u64 v[20:21], s[2:3], 0, v[22:23]
	v_readfirstlane_b32 s2, v155
	s_mov_b32 m0, s2
	v_ashrrev_i32_e32 v19, 8, v0
	global_load_lds_dwordx4 v[20:21], off
	s_waitcnt lgkmcnt(0)
	s_barrier
	v_cmp_gt_i32_e32 vcc, s96, v162
	s_and_saveexec_b64 s[98:99], vcc
	s_cbranch_execz .Lrs_skipN
	v_add_u32_e32 v186, s56, v162
	v_ashrrev_i32_e32 v187, 31, v186
	v_readlane_b32 s2, v253, 34
	v_lshlrev_b64 v[186:187], 6, v[186:187]
	v_readlane_b32 s3, v253, 35
	v_lshl_add_u32 v184, v162, 2, v177
	s_nop 0
	v_lshl_add_u64 v[198:199], s[2:3], 0, v[186:187]
	global_load_dwordx4 v[186:189], v[198:199], off offset:48
	global_load_dwordx4 v[190:193], v[198:199], off offset:32
	global_load_dwordx4 v[194:197], v[198:199], off offset:16
	s_nop 0
	global_load_dwordx4 v[198:201], v[198:199], off
	s_waitcnt vmcnt(2)
	v_add_f32_e32 v190, v190, v191
	v_add_f32_e32 v192, v192, v193
	s_waitcnt vmcnt(0)
	v_mov_b32_e32 v202, v199
	v_mov_b32_e32 v203, v200
	v_mov_b32_e32 v199, v201
	v_mov_b32_e32 v200, v195
	v_mov_b32_e32 v201, v196
	v_mov_b32_e32 v195, v197
	v_pk_add_f32 v[198:199], v[202:203], v[198:199]
	v_pk_add_f32 v[194:195], v[200:201], v[194:195]
	v_pk_add_f32 v[198:199], v[198:199], v[198:199] op_sel:[0,1] op_sel_hi:[1,0]
	v_pk_add_f32 v[194:195], v[194:195], v[194:195] op_sel:[0,1] op_sel_hi:[1,0]
	v_mov_b32_e32 v199, v186
	v_mov_b32_e32 v195, v187
	v_mov_b32_e32 v191, v188
	v_mov_b32_e32 v193, v189
	v_pk_add_f32 v[186:187], v[198:199], v[194:195]
	v_pk_add_f32 v[188:189], v[190:191], v[192:193]
	s_nop 0
	v_pk_add_f32 v[186:187], v[186:187], v[188:189]
	s_nop 0
	v_add_f32_e32 v186, v186, v187
	v_fmamk_f32 v186, v186, 0x3a800000, v163
	v_rsq_f32_e32 v186, v186
	ds_write_b32 v184, v186
.Lrs_skipN:
	s_or_b64 exec, exec, s[98:99]
	v_cmp_eq_u32_e32 vcc, 1, v19
	s_and_saveexec_b64 s[10:11], vcc
	s_cbranch_execz .LBB0_177
	s_barrier

; DI int tid() { int t = __builtin_amdgcn_workitem_id_x(); asm volatile("" : "+v"(t)); return t; }
; #define STAGE(P, BASE, br, kt) do { const bf16_t* g_ = (BASE) + (size_t)(br) * K + (size_t)(kt) * 64; \
;         _Pragma("unroll") for (int i_ = 0; i_ < 2; ++i_) \
;             __builtin_amdgcn_global_load_lds((const unsigned*)(g_ + gofs[i_]), (lds_ptr_t)((P) + wb + i_ * 8192), 16, 0, 0); } while (0)
; #define BAR __builtin_amdgcn_s_barrier()
; #define STAGE(P, BASE, br, kt) do { const int sg_ = (kt) >> 3; const bf16_t* g_ = (sg_ == 0 ? BASE##0 : sg_ == 1 ? BASE##1 : BASE##2) + (size_t)(br) * K + (size_t)((kt) & 7) * 64; \
;         _Pragma("unroll") for (int i_ = 0; i_ < 2; ++i_) \
;             __builtin_amdgcn_global_load_lds((const unsigned*)(g_ + gofs[i_]), (lds_ptr_t)((P) + wb + i_ * 8192), 16, 0, 0); } while (0)
; #define BAR __builtin_amdgcn_s_barrier()
; DI void gemm8(f32x4 (&acc)[2][2][4][2], const bf16_t* __restrict__ Rm, const bf16_t* __restrict__ Cm, int K, char* shm) {
;     ...
;     for (int i = 0; i < 2; ++i) { int r_, c_; stage_rc(t * 16 + i * 8192, r_, c_); gofs[i] = r_ * K + c_; }
;     const int wb = wid * 1024;
;     ...
; #pragma unroll
;     for (int a_ = 0; a_ < 2; ++a_)
; #pragma unroll
;         for (int b_ = 0; b_ < 2; ++b_)
; #pragma unroll
;             for (int m = 0; m < 4; ++m) { acc[a_][b_][m][0] = (f32x4){0.f, 0.f, 0.f, 0.f}; acc[a_][b_][m][1] = (f32x4){0.f, 0.f, 0.f, 0.f}; }
;     bf16x8 At[4][2], B0[2][2], B1[2][2];
;     const int nt = K >> 6;
;     STAGE(SB(0, 0), Cm, 0, 0); STAGE(SA(0, 0), Rm, 0, 0);
;     STAGE(SB(0, 1), Cm, 128, 0); STAGE(SA(0, 1), Rm, 128, 0);
;     if (wr == 1) BAR;
; DI void tile_rstd(const float* __restrict__ ssq, int m0, char* lds) {
;     __syncthreads();
;     const int t = tid();
;     if (t < 256) {
;         const f32x4* p = (const f32x4*)(ssq + (size_t)(m0 + t) * 16);
;         const f32x4 a = p[0], b = p[1], c = p[2], d = p[3];
;         const float sm = ((a[0] + a[1]) + (a[2] + a[3])) + ((b[0] + b[1]) + (b[2] + b[3])) + ((c[0] + c[1]) + (c[2] + c[3])) + ((d[0] + d[1]) + (d[2] + d[3]));
;         ((float*)(lds + LDS_RS))[t] = __builtin_amdgcn_rsqf(sm * (1.f / 1024.f) + kEps);
;     }
.LBB0_310:
	s_and_b64 vcc, exec, s[6:7]
	s_cbranch_vccz .LBB0_171
	v_mov_b32_e32 v0, v162
	s_lshl_b32 s2, s15, 19
	v_ashrrev_i32_e32 v3, 31, v0
	v_lshrrev_b32_e32 v3, 26, v3
	v_add_u32_e32 v3, v0, v3
	v_ashrrev_i32_e32 v10, 6, v3
	v_bfe_i32 v3, v0, 27, 1
	v_lshlrev_b32_e32 v2, 4, v0
	v_lshrrev_b32_e32 v3, 22, v3
	v_add_u32_e32 v3, v2, v3
	v_and_b32_e32 v3, 0xfffffc00, v3
	v_sub_u32_e32 v3, v2, v3
	v_lshrrev_b32_e32 v4, 4, v3
	v_bitop3_b32 v4, v4, v3, 32 bitop3:0x6c
	v_ashrrev_i32_e32 v3, 31, v3
	v_lshrrev_b32_e32 v3, 26, v3
	v_lshlrev_b32_e32 v5, 3, v10
	v_add_u32_e32 v3, v4, v3
	v_and_b32_e32 v5, 0x3ffff0, v5
	v_ashrrev_i32_e32 v11, 6, v3
	v_add_u32_e32 v3, v11, v5
	v_lshlrev_b32_e32 v5, 5, v10
	v_and_b32_e32 v12, 32, v5
	v_mul_i32_i24_e32 v5, 64, v11
	v_sub_u32_e32 v4, v4, v5
	v_ashrrev_i16_sdwa v13, v175, sext(v4) dst_sel:DWORD dst_unused:UNUSED_PAD src0_sel:DWORD src1_sel:BYTE_0
	v_lshl_or_b32 v3, v3, 10, v12
	v_add_u32_e32 v2, 0x2000, v2
	v_add_u32_sdwa v130, v3, sext(v13) dst_sel:DWORD dst_unused:UNUSED_PAD src0_sel:DWORD src1_sel:WORD_0
	v_ashrrev_i32_e32 v3, 31, v2
	v_lshrrev_b32_e32 v3, 22, v3
	v_add_u32_e32 v3, v2, v3
	v_ashrrev_i32_e32 v14, 10, v3
	v_mul_i32_i24_e32 v3, 0x400, v14
	v_sub_u32_e32 v2, v2, v3
	v_lshrrev_b32_e32 v3, 4, v2
	v_bitop3_b32 v2, v3, v2, 32 bitop3:0x6c
	v_ashrrev_i32_e32 v4, 31, v2
	v_lshrrev_b32_e32 v4, 26, v4
	v_lshlrev_b32_e32 v3, 3, v14
	v_add_u32_e32 v4, v2, v4
	v_and_b32_e32 v3, 0x3ffff0, v3
	v_ashrrev_i32_e32 v16, 6, v4
	v_lshlrev_b32_e32 v5, 5, v14
	v_and_b32_e32 v4, 0xc0, v4
	s_add_u32 s6, s34, s2
	v_ashrrev_i32_e32 v15, 6, v0
	v_add_u32_e32 v3, v16, v3
	v_and_b32_e32 v17, 32, v5
	v_sub_u32_e32 v2, v2, v4
	s_addc_u32 s7, s28, 0
	s_lshl_b64 s[2:3], s[82:83], 11
	v_ashrrev_i16_sdwa v18, v175, sext(v2) dst_sel:DWORD dst_unused:UNUSED_PAD src0_sel:DWORD src1_sel:BYTE_0
	v_lshl_or_b32 v2, v3, 10, v17
	s_waitcnt lgkmcnt(3)
	v_lshlrev_b32_e32 v146, 10, v15
	s_add_u32 s8, s31, s2
	v_add_u32_sdwa v132, v2, sext(v18) dst_sel:DWORD dst_unused:UNUSED_PAD src0_sel:DWORD src1_sel:WORD_0
	v_add_u32_e32 v147, 0x10000, v146
	v_ashrrev_i32_e32 v131, 31, v130
	s_addc_u32 s9, s54, s3
	v_lshlrev_b64 v[20:21], 1, v[130:131]
	v_readfirstlane_b32 s2, v147
	v_ashrrev_i32_e32 v133, 31, v132
	v_add_u32_e32 v148, 0x12000, v146
	v_lshl_add_u64 v[2:3], s[8:9], 0, v[20:21]
	s_mov_b32 m0, s2
	v_lshlrev_b64 v[22:23], 1, v[132:133]
	v_readfirstlane_b32 s2, v148
	global_load_lds_dwordx4 v[2:3], off
	v_lshl_add_u64 v[6:7], s[8:9], 0, v[22:23]
	s_mov_b32 m0, s2
	v_readfirstlane_b32 s2, v146
	v_add_u32_e32 v150, 0x2000, v146
	global_load_lds_dwordx4 v[6:7], off
	v_lshl_add_u64 v[8:9], s[6:7], 0, v[20:21]
	s_mov_b32 m0, s2
	v_readfirstlane_b32 s2, v150
	global_load_lds_dwordx4 v[8:9], off
	s_mov_b32 m0, s2
	s_add_u32 s2, s8, 0x40000
	v_add_u32_e32 v151, 0x14000, v146
	v_lshl_add_u64 v[4:5], s[6:7], 0, v[22:23]
	s_addc_u32 s3, s9, 0
	v_readfirstlane_b32 s10, v151
	global_load_lds_dwordx4 v[4:5], off
	v_lshl_add_u64 v[24:25], s[2:3], 0, v[20:21]
	s_mov_b32 m0, s10
	v_add_u32_e32 v152, 0x16000, v146
	global_load_lds_dwordx4 v[24:25], off
	v_lshl_add_u64 v[24:25], s[2:3], 0, v[22:23]
	v_readfirstlane_b32 s2, v152
	s_mov_b32 m0, s2
	s_add_u32 s2, s6, 0x40000
	v_add_u32_e32 v153, 0x4000, v146
	s_addc_u32 s3, s7, 0
	v_readfirstlane_b32 s10, v153
	global_load_lds_dwordx4 v[24:25], off
	v_lshl_add_u64 v[20:21], s[2:3], 0, v[20:21]
	s_mov_b32 m0, s10
	v_add_u32_e32 v155, 0x6000, v146
	global_load_lds_dwordx4 v[20:21], off
	v_lshl_add_u64 v[20:21], s[2:3], 0, v[22:23]
	v_readfirstlane_b32 s2, v155
	s_mov_b32 m0, s2
	v_ashrrev_i32_e32 v19, 8, v0
	global_load_lds_dwordx4 v[20:21], off
	s_waitcnt lgkmcnt(0)
	s_barrier
	v_cmp_gt_i32_e32 vcc, s96, v162
	s_and_saveexec_b64 s[98:99], vcc
	s_cbranch_execz .Lrs_skipV
	v_add_u32_e32 v186, s56, v162
	v_ashrrev_i32_e32 v187, 31, v186
	v_readlane_b32 s2, v253, 34
	v_lshlrev_b64 v[186:187], 6, v[186:187]
	v_readlane_b32 s3, v253, 35
	v_lshl_add_u32 v184, v162, 2, v177
	s_nop 0
	v_lshl_add_u64 v[198:199], s[2:3], 0, v[186:187]
	global_load_dwordx4 v[186:189], v[198:199], off offset:48
	global_load_dwordx4 v[190:193], v[198:199], off offset:32
	global_load_dwordx4 v[194:197], v[198:199], off offset:16
	s_nop 0
	global_load_dwordx4 v[198:201], v[198:199], off
	s_waitcnt vmcnt(2)
	v_add_f32_e32 v190, v190, v191
	v_add_f32_e32 v192, v192, v193
	s_waitcnt vmcnt(0)
	v_mov_b32_e32 v202, v199
	v_mov_b32_e32 v203, v200
	v_mov_b32_e32 v199, v201
	v_mov_b32_e32 v200, v195
	v_mov_b32_e32 v201, v196
	v_mov_b32_e32 v195, v197
	v_pk_add_f32 v[198:199], v[202:203], v[198:199]
	v_pk_add_f32 v[194:195], v[200:201], v[194:195]
	v_pk_add_f32 v[198:199], v[198:199], v[198:199] op_sel:[0,1] op_sel_hi:[1,0]
	v_pk_add_f32 v[194:195], v[194:195], v[194:195] op_sel:[0,1] op_sel_hi:[1,0]
	v_mov_b32_e32 v199, v186
	v_mov_b32_e32 v195, v187
	v_mov_b32_e32 v191, v188
	v_mov_b32_e32 v193, v189
	v_pk_add_f32 v[186:187], v[198:199], v[194:195]
	v_pk_add_f32 v[188:189], v[190:191], v[192:193]
	s_nop 0
	v_pk_add_f32 v[186:187], v[186:187], v[188:189]
	s_nop 0
	v_add_f32_e32 v186, v186, v187
	v_fmamk_f32 v186, v186, 0x3a800000, v163
	v_rsq_f32_e32 v186, v186
	ds_write_b32 v184, v186
